# tile headers: accumulator zeroing with 64-bit moves (63 v_mov_b64 instead of 126 v_mov_b32 per tile)
# baseline (speedup 1.0000x reference)
.LBB0_146:
	s_ashr_i32 s11, s10, 31
	v_cmp_lt_i64_e32 vcc, s[12:13], v[140:141]
	s_lshl_b64 s[12:13], s[10:11], 20
	s_add_u32 s12, s80, s12
	s_addc_u32 s13, s81, s13
	s_and_b64 s[14:15], vcc, exec
	s_cselect_b32 s11, s13, s17
	s_cselect_b32 s41, s12, s16
	s_ashr_i32 s9, s8, 31
	s_lshl_b64 s[14:15], s[8:9], 20
	s_add_u32 s14, s22, s14
	s_addc_u32 s15, s23, s15
	s_and_b64 s[20:21], vcc, exec
	s_cselect_b32 s9, s15, s19
	s_cselect_b32 s44, s14, s18
	s_add_u32 s16, s16, 0x80080
	s_addc_u32 s17, s17, 0
	s_add_u32 s45, s18, 0x100
	v_mov_b32_e32 v0, 0
	s_addc_u32 s46, s19, 0
	s_mov_b32 s47, -2
	v_mov_b32_e32 v1, v0
	v_mov_b64_e32 v[2:3], 0
	v_mov_b64_e32 v[4:5], 0
	v_mov_b64_e32 v[6:7], 0
	v_mov_b64_e32 v[16:17], 0
	s_waitcnt vmcnt(0)
	v_mov_b64_e32 v[18:19], 0
	v_mov_b64_e32 v[20:21], 0
	v_mov_b64_e32 v[22:23], 0
	v_mov_b64_e32 v[32:33], 0
	v_mov_b64_e32 v[34:35], 0
	v_mov_b64_e32 v[36:37], 0
	v_mov_b64_e32 v[38:39], 0
	v_mov_b64_e32 v[48:49], 0
	v_mov_b64_e32 v[50:51], 0
	v_mov_b64_e32 v[52:53], 0
	v_mov_b64_e32 v[54:55], 0
	v_mov_b64_e32 v[8:9], 0
	v_mov_b64_e32 v[10:11], 0
	v_mov_b64_e32 v[12:13], 0
	v_mov_b64_e32 v[14:15], 0
	v_mov_b64_e32 v[24:25], 0
	v_mov_b64_e32 v[26:27], 0
	v_mov_b64_e32 v[28:29], 0
	v_mov_b64_e32 v[30:31], 0
	v_mov_b64_e32 v[40:41], 0
	v_mov_b64_e32 v[42:43], 0
	v_mov_b64_e32 v[44:45], 0
	v_mov_b64_e32 v[46:47], 0
	v_mov_b64_e32 v[56:57], 0
	v_mov_b64_e32 v[58:59], 0
	v_mov_b64_e32 v[60:61], 0
	v_mov_b64_e32 v[62:63], 0
	v_mov_b64_e32 v[64:65], 0
	v_mov_b64_e32 v[66:67], 0
	v_mov_b64_e32 v[68:69], 0
	v_mov_b64_e32 v[70:71], 0
	v_mov_b64_e32 v[80:81], 0
	v_mov_b64_e32 v[82:83], 0
	v_mov_b64_e32 v[84:85], 0
	v_mov_b64_e32 v[86:87], 0
	v_mov_b64_e32 v[96:97], 0
	v_mov_b64_e32 v[98:99], 0
	v_mov_b64_e32 v[100:101], 0
	v_mov_b64_e32 v[102:103], 0
	v_mov_b64_e32 v[112:113], 0
	v_mov_b64_e32 v[114:115], 0
	v_mov_b64_e32 v[116:117], 0
	v_mov_b64_e32 v[118:119], 0
	v_mov_b64_e32 v[72:73], 0
	v_mov_b64_e32 v[74:75], 0
	v_mov_b64_e32 v[76:77], 0
	v_mov_b64_e32 v[78:79], 0
	v_mov_b64_e32 v[88:89], 0
	v_mov_b64_e32 v[90:91], 0
	v_mov_b64_e32 v[92:93], 0
	v_mov_b64_e32 v[94:95], 0
	v_mov_b64_e32 v[104:105], 0
	v_mov_b64_e32 v[106:107], 0
	v_mov_b64_e32 v[108:109], 0
	v_mov_b64_e32 v[110:111], 0
	v_mov_b64_e32 v[120:121], 0
	v_mov_b64_e32 v[122:123], 0
	v_mov_b64_e32 v[124:125], 0
	v_mov_b64_e32 v[126:127], 0
	v_xor_b32_e32 v220, 64, v165
	v_xor_b32_e32 v221, 64, v166
	v_xor_b32_e32 v234, 64, v167
	v_add_u32_e32 v235, 0x18000, v161
	v_xor_b32_e32 v236, 64, v235
	s_cmpk_lt_u32 s3, 0x100
	s_cbranch_scc1 .Lst_in_s1
	s_barrier

.LBB0_282:
	s_ashr_i32 s11, s10, 31
	s_lshl_b64 s[16:17], s[10:11], 20
	s_add_u32 s16, s22, s16
	s_addc_u32 s17, s23, s17
	s_and_b64 s[6:7], s[6:7], exec
	s_cselect_b32 s1, s17, s19
	s_cselect_b32 s11, s16, s18
	s_add_u32 s6, s20, 0x180080
	s_addc_u32 s7, s21, 0
	s_add_u32 s43, s18, 0x100
	v_mov_b32_e32 v0, 0
	s_addc_u32 s44, s19, 0
	s_mov_b32 s45, -2
	s_waitcnt lgkmcnt(0)
	v_mov_b32_e32 v1, v0
	v_mov_b64_e32 v[2:3], 0
	v_mov_b64_e32 v[4:5], 0
	v_mov_b64_e32 v[6:7], 0
	s_waitcnt vmcnt(0)
	v_mov_b64_e32 v[16:17], 0
	v_mov_b64_e32 v[18:19], 0
	v_mov_b64_e32 v[20:21], 0
	v_mov_b64_e32 v[22:23], 0
	v_mov_b64_e32 v[32:33], 0
	v_mov_b64_e32 v[34:35], 0
	v_mov_b64_e32 v[36:37], 0
	v_mov_b64_e32 v[38:39], 0
	v_mov_b64_e32 v[48:49], 0
	v_mov_b64_e32 v[50:51], 0
	v_mov_b64_e32 v[52:53], 0
	v_mov_b64_e32 v[54:55], 0
	v_mov_b64_e32 v[8:9], 0
	v_mov_b64_e32 v[10:11], 0
	v_mov_b64_e32 v[12:13], 0
	v_mov_b64_e32 v[14:15], 0
	v_mov_b64_e32 v[24:25], 0
	v_mov_b64_e32 v[26:27], 0
	v_mov_b64_e32 v[28:29], 0
	v_mov_b64_e32 v[30:31], 0
	v_mov_b64_e32 v[40:41], 0
	v_mov_b64_e32 v[42:43], 0
	v_mov_b64_e32 v[44:45], 0
	v_mov_b64_e32 v[46:47], 0
	v_mov_b64_e32 v[56:57], 0
	v_mov_b64_e32 v[58:59], 0
	v_mov_b64_e32 v[60:61], 0
	v_mov_b64_e32 v[62:63], 0
	v_mov_b64_e32 v[64:65], 0
	v_mov_b64_e32 v[66:67], 0
	v_mov_b64_e32 v[68:69], 0
	v_mov_b64_e32 v[70:71], 0
	v_mov_b64_e32 v[80:81], 0
	v_mov_b64_e32 v[82:83], 0
	v_mov_b64_e32 v[84:85], 0
	v_mov_b64_e32 v[86:87], 0
	v_mov_b64_e32 v[96:97], 0
	v_mov_b64_e32 v[98:99], 0
	v_mov_b64_e32 v[100:101], 0
	v_mov_b64_e32 v[102:103], 0
	v_mov_b64_e32 v[112:113], 0
	v_mov_b64_e32 v[114:115], 0
	v_mov_b64_e32 v[116:117], 0
	v_mov_b64_e32 v[118:119], 0
	v_mov_b64_e32 v[72:73], 0
	v_mov_b64_e32 v[74:75], 0
	v_mov_b64_e32 v[76:77], 0
	v_mov_b64_e32 v[78:79], 0
	v_mov_b64_e32 v[88:89], 0
	v_mov_b64_e32 v[90:91], 0
	v_mov_b64_e32 v[92:93], 0
	v_mov_b64_e32 v[94:95], 0
	v_mov_b64_e32 v[104:105], 0
	v_mov_b64_e32 v[106:107], 0
	v_mov_b64_e32 v[108:109], 0
	v_mov_b64_e32 v[110:111], 0
	v_mov_b64_e32 v[120:121], 0
	v_mov_b64_e32 v[122:123], 0
	v_mov_b64_e32 v[124:125], 0
	v_mov_b64_e32 v[126:127], 0
	v_xor_b32_e32 v150, 64, v146
	v_xor_b32_e32 v151, 64, v147
	v_xor_b32_e32 v216, 64, v148
	v_add_u32_e32 v217, 0x18000, v145
	v_xor_b32_e32 v220, 64, v217
	s_cmpk_lt_u32 s3, 0x100
	s_cbranch_scc1 .Lst_in_s2
	s_barrier

.LBB0_362:
	s_ashr_i32 s31, s30, 31
	v_cmp_lt_i64_e32 vcc, s[10:11], v[176:177]
	s_lshl_b64 s[10:11], s[30:31], 20
	s_add_u32 s34, s80, s10
	s_addc_u32 s35, s81, s11
	s_and_b64 s[10:11], vcc, exec
	s_cselect_b32 s31, s35, s7
	s_cselect_b32 s33, s34, s6
	s_ashr_i32 s29, s28, 31
	s_lshl_b64 s[10:11], s[28:29], 19
	s_add_u32 s36, s40, s10
	s_addc_u32 s37, s41, s11
	s_and_b64 s[10:11], vcc, exec
	s_cselect_b32 s29, s37, s9
	s_cselect_b32 s62, s36, s8
	s_add_u32 s63, s8, 0x100
	v_mov_b32_e32 v0, 0
	s_addc_u32 s64, s9, 0
	s_mov_b32 s65, -2
	v_mov_b32_e32 v1, v0
	v_mov_b64_e32 v[2:3], 0
	v_mov_b64_e32 v[64:65], 0
	v_mov_b64_e32 v[66:67], 0
	v_mov_b64_e32 v[8:9], 0
	s_waitcnt vmcnt(0)
	v_mov_b64_e32 v[10:11], 0
	v_mov_b64_e32 v[68:69], 0
	v_mov_b64_e32 v[70:71], 0
	v_mov_b64_e32 v[12:13], 0
	v_mov_b64_e32 v[14:15], 0
	v_mov_b64_e32 v[110:111], 0
	v_mov_b64_e32 v[112:113], 0
	v_mov_b64_e32 v[16:17], 0
	v_mov_b64_e32 v[18:19], 0
	v_mov_b64_e32 v[118:119], 0
	v_mov_b64_e32 v[120:121], 0
	v_mov_b64_e32 v[4:5], 0
	v_mov_b64_e32 v[6:7], 0
	v_mov_b64_e32 v[72:73], 0
	v_mov_b64_e32 v[74:75], 0
	v_mov_b64_e32 v[20:21], 0
	v_mov_b64_e32 v[22:23], 0
	v_mov_b64_e32 v[114:115], 0
	v_mov_b64_e32 v[116:117], 0
	v_mov_b64_e32 v[24:25], 0
	v_mov_b64_e32 v[26:27], 0
	v_mov_b64_e32 v[122:123], 0
	v_mov_b64_e32 v[124:125], 0
	v_mov_b64_e32 v[28:29], 0
	v_mov_b64_e32 v[30:31], 0
	v_mov_b64_e32 v[126:127], 0
	v_mov_b64_e32 v[128:129], 0
	v_mov_b64_e32 v[32:33], 0
	v_mov_b64_e32 v[34:35], 0
	v_mov_b64_e32 v[130:131], 0
	v_mov_b64_e32 v[132:133], 0
	v_mov_b64_e32 v[36:37], 0
	v_mov_b64_e32 v[38:39], 0
	v_mov_b64_e32 v[134:135], 0
	v_mov_b64_e32 v[136:137], 0
	v_mov_b64_e32 v[44:45], 0
	v_mov_b64_e32 v[46:47], 0
	v_mov_b64_e32 v[142:143], 0
	v_mov_b64_e32 v[144:145], 0
	v_mov_b64_e32 v[56:57], 0
	v_mov_b64_e32 v[58:59], 0
	v_mov_b64_e32 v[154:155], 0
	v_mov_b64_e32 v[156:157], 0
	v_mov_b64_e32 v[40:41], 0
	v_mov_b64_e32 v[42:43], 0
	v_mov_b64_e32 v[138:139], 0
	v_mov_b64_e32 v[140:141], 0
	v_mov_b64_e32 v[48:49], 0
	v_mov_b64_e32 v[50:51], 0
	v_mov_b64_e32 v[146:147], 0
	v_mov_b64_e32 v[148:149], 0
	v_mov_b64_e32 v[52:53], 0
	v_mov_b64_e32 v[54:55], 0
	v_mov_b64_e32 v[150:151], 0
	v_mov_b64_e32 v[152:153], 0
	v_mov_b64_e32 v[60:61], 0
	v_mov_b64_e32 v[62:63], 0
	v_mov_b64_e32 v[158:159], 0
	v_mov_b64_e32 v[160:161], 0
	v_xor_b32_e32 v216, 64, v231
	v_xor_b32_e32 v217, 64, v241
	v_xor_b32_e32 v244, 64, v242
	v_add_u32_e32 v245, 0x18000, v229
	v_xor_b32_e32 v246, 64, v245
	v_add_u32_e32 v247, 0x1c000, v229
	v_xor_b32_e32 v248, 64, v247
	s_cmpk_lt_u32 s3, 0x100
	s_cbranch_scc1 .Lst_in_s3
	s_barrier

.LBB0_507:
	s_add_u32 s0, s0, 0x160080
	s_addc_u32 s1, s1, 0
	s_add_u32 s39, s16, 0x100
	v_mov_b32_e32 v0, 0
	s_addc_u32 s40, s17, 0
	s_mov_b32 s41, -2
	s_waitcnt lgkmcnt(0)
	v_mov_b32_e32 v1, v0
	v_mov_b64_e32 v[2:3], 0
	v_mov_b64_e32 v[4:5], 0
	v_mov_b64_e32 v[6:7], 0
	s_waitcnt vmcnt(0)
	v_mov_b64_e32 v[16:17], 0
	v_mov_b64_e32 v[18:19], 0
	v_mov_b64_e32 v[20:21], 0
	v_mov_b64_e32 v[22:23], 0
	v_mov_b64_e32 v[32:33], 0
	v_mov_b64_e32 v[34:35], 0
	v_mov_b64_e32 v[36:37], 0
	v_mov_b64_e32 v[38:39], 0
	v_mov_b64_e32 v[48:49], 0
	v_mov_b64_e32 v[50:51], 0
	v_mov_b64_e32 v[52:53], 0
	v_mov_b64_e32 v[54:55], 0
	v_mov_b64_e32 v[8:9], 0
	v_mov_b64_e32 v[10:11], 0
	v_mov_b64_e32 v[12:13], 0
	v_mov_b64_e32 v[14:15], 0
	v_mov_b64_e32 v[24:25], 0
	v_mov_b64_e32 v[26:27], 0
	v_mov_b64_e32 v[28:29], 0
	v_mov_b64_e32 v[30:31], 0
	v_mov_b64_e32 v[40:41], 0
	v_mov_b64_e32 v[42:43], 0
	v_mov_b64_e32 v[44:45], 0
	v_mov_b64_e32 v[46:47], 0
	v_mov_b64_e32 v[56:57], 0
	v_mov_b64_e32 v[58:59], 0
	v_mov_b64_e32 v[60:61], 0
	v_mov_b64_e32 v[62:63], 0
	v_mov_b64_e32 v[64:65], 0
	v_mov_b64_e32 v[66:67], 0
	v_mov_b64_e32 v[68:69], 0
	v_mov_b64_e32 v[70:71], 0
	v_mov_b64_e32 v[80:81], 0
	v_mov_b64_e32 v[82:83], 0
	v_mov_b64_e32 v[84:85], 0
	v_mov_b64_e32 v[86:87], 0
	v_mov_b64_e32 v[96:97], 0
	v_mov_b64_e32 v[98:99], 0
	v_mov_b64_e32 v[100:101], 0
	v_mov_b64_e32 v[102:103], 0
	v_mov_b64_e32 v[112:113], 0
	v_mov_b64_e32 v[114:115], 0
	v_mov_b64_e32 v[116:117], 0
	v_mov_b64_e32 v[118:119], 0
	v_mov_b64_e32 v[72:73], 0
	v_mov_b64_e32 v[74:75], 0
	v_mov_b64_e32 v[76:77], 0
	v_mov_b64_e32 v[78:79], 0
	v_mov_b64_e32 v[88:89], 0
	v_mov_b64_e32 v[90:91], 0
	v_mov_b64_e32 v[92:93], 0
	v_mov_b64_e32 v[94:95], 0
	v_mov_b64_e32 v[104:105], 0
	v_mov_b64_e32 v[106:107], 0
	v_mov_b64_e32 v[108:109], 0
	v_mov_b64_e32 v[110:111], 0
	v_mov_b64_e32 v[120:121], 0
	v_mov_b64_e32 v[122:123], 0
	v_mov_b64_e32 v[124:125], 0
	v_mov_b64_e32 v[126:127], 0
	v_xor_b32_e32 v216, 64, v141
	v_xor_b32_e32 v217, 64, v142
	v_xor_b32_e32 v244, 64, v143
	v_add_u32_e32 v245, 0x18000, v140
	v_xor_b32_e32 v246, 64, v245
	s_cmpk_lt_u32 s3, 0x100
	s_cbranch_scc1 .Lst_in_s4
	s_barrier

.LBB0_598:
	s_ashr_i32 s21, s20, 31
	v_cmp_lt_i64_e32 vcc, s[22:23], v[136:137]
	s_lshl_b64 s[22:23], s[20:21], 20
	s_add_u32 s22, s80, s22
	s_addc_u32 s23, s81, s23
	s_and_b64 s[24:25], vcc, exec
	s_cselect_b32 s1, s23, s27
	s_cselect_b32 s13, s22, s26
	s_ashr_i32 s19, s18, 31
	s_lshl_b64 s[24:25], s[18:19], 20
	s_add_u32 s24, s34, s24
	s_addc_u32 s25, s35, s25
	s_and_b64 s[30:31], vcc, exec
	s_cselect_b32 s19, s25, s29
	s_cselect_b32 s21, s24, s28
	s_add_u32 s26, s26, 0x80080
	s_addc_u32 s27, s27, 0
	s_add_u32 s33, s28, 0x100
	v_mov_b32_e32 v0, 0
	s_addc_u32 s48, s29, 0
	s_mov_b32 s49, -2
	s_waitcnt lgkmcnt(0)
	v_mov_b32_e32 v1, v0
	v_mov_b64_e32 v[2:3], 0
	v_mov_b64_e32 v[4:5], 0
	v_mov_b64_e32 v[6:7], 0
	s_waitcnt vmcnt(0)
	v_mov_b64_e32 v[16:17], 0
	v_mov_b64_e32 v[18:19], 0
	v_mov_b64_e32 v[20:21], 0
	v_mov_b64_e32 v[22:23], 0
	v_mov_b64_e32 v[32:33], 0
	v_mov_b64_e32 v[34:35], 0
	v_mov_b64_e32 v[36:37], 0
	v_mov_b64_e32 v[38:39], 0
	v_mov_b64_e32 v[48:49], 0
	v_mov_b64_e32 v[50:51], 0
	v_mov_b64_e32 v[52:53], 0
	v_mov_b64_e32 v[54:55], 0
	v_mov_b64_e32 v[8:9], 0
	v_mov_b64_e32 v[10:11], 0
	v_mov_b64_e32 v[12:13], 0
	v_mov_b64_e32 v[14:15], 0
	v_mov_b64_e32 v[24:25], 0
	v_mov_b64_e32 v[26:27], 0
	v_mov_b64_e32 v[28:29], 0
	v_mov_b64_e32 v[30:31], 0
	v_mov_b64_e32 v[40:41], 0
	v_mov_b64_e32 v[42:43], 0
	v_mov_b64_e32 v[44:45], 0
	v_mov_b64_e32 v[46:47], 0
	v_mov_b64_e32 v[56:57], 0
	v_mov_b64_e32 v[58:59], 0
	v_mov_b64_e32 v[60:61], 0
	v_mov_b64_e32 v[62:63], 0
	v_mov_b64_e32 v[64:65], 0
	v_mov_b64_e32 v[66:67], 0
	v_mov_b64_e32 v[68:69], 0
	v_mov_b64_e32 v[70:71], 0
	v_mov_b64_e32 v[80:81], 0
	v_mov_b64_e32 v[82:83], 0
	v_mov_b64_e32 v[84:85], 0
	v_mov_b64_e32 v[86:87], 0
	v_mov_b64_e32 v[96:97], 0
	v_mov_b64_e32 v[98:99], 0
	v_mov_b64_e32 v[100:101], 0
	v_mov_b64_e32 v[102:103], 0
	v_mov_b64_e32 v[112:113], 0
	v_mov_b64_e32 v[114:115], 0
	v_mov_b64_e32 v[116:117], 0
	v_mov_b64_e32 v[118:119], 0
	v_mov_b64_e32 v[72:73], 0
	v_mov_b64_e32 v[74:75], 0
	v_mov_b64_e32 v[76:77], 0
	v_mov_b64_e32 v[78:79], 0
	v_mov_b64_e32 v[88:89], 0
	v_mov_b64_e32 v[90:91], 0
	v_mov_b64_e32 v[92:93], 0
	v_mov_b64_e32 v[94:95], 0
	v_mov_b64_e32 v[104:105], 0
	v_mov_b64_e32 v[106:107], 0
	v_mov_b64_e32 v[108:109], 0
	v_mov_b64_e32 v[110:111], 0
	v_mov_b64_e32 v[120:121], 0
	v_mov_b64_e32 v[122:123], 0
	v_mov_b64_e32 v[124:125], 0
	v_mov_b64_e32 v[126:127], 0
	v_xor_b32_e32 v144, 64, v149
	v_xor_b32_e32 v145, 64, v150
	v_xor_b32_e32 v216, 64, v151
	v_add_u32_e32 v217, 0x18000, v147
	v_xor_b32_e32 v234, 64, v217
	v_add_u32_e32 v235, 0x1c000, v147
	v_xor_b32_e32 v252, 64, v235
	s_cmpk_lt_u32 s3, 0x100
	s_cbranch_scc1 .Lst_in_s5
	s_barrier

.LBB0_759:
	s_ashr_i32 s15, s14, 31
	v_cmp_lt_i64_e32 vcc, s[16:17], v[136:137]
	s_lshl_b64 s[16:17], s[14:15], 21
	s_add_u32 s16, s96, s16
	s_addc_u32 s17, s97, s17
	s_and_b64 s[18:19], vcc, exec
	s_cselect_b32 s1, s17, s21
	s_cselect_b32 s9, s16, s20
	s_ashr_i32 s13, s12, 31
	s_lshl_b64 s[18:19], s[12:13], 20
	s_add_u32 s18, s26, s18
	s_addc_u32 s19, s27, s19
	s_and_b64 s[24:25], vcc, exec
	s_cselect_b32 s13, s19, s23
	s_cselect_b32 s15, s18, s22
	s_add_u32 s20, s20, 0x100080
	s_addc_u32 s21, s21, 0
	s_add_u32 s43, s22, 0x100
	v_mov_b32_e32 v0, 0
	s_addc_u32 s44, s23, 0
	s_mov_b32 s45, -2
	s_waitcnt lgkmcnt(0)
	v_mov_b32_e32 v1, v0
	v_mov_b64_e32 v[2:3], 0
	v_mov_b64_e32 v[4:5], 0
	v_mov_b64_e32 v[6:7], 0
	s_waitcnt vmcnt(0)
	v_mov_b64_e32 v[16:17], 0
	v_mov_b64_e32 v[18:19], 0
	v_mov_b64_e32 v[20:21], 0
	v_mov_b64_e32 v[22:23], 0
	v_mov_b64_e32 v[32:33], 0
	v_mov_b64_e32 v[34:35], 0
	v_mov_b64_e32 v[36:37], 0
	v_mov_b64_e32 v[38:39], 0
	v_mov_b64_e32 v[48:49], 0
	v_mov_b64_e32 v[50:51], 0
	v_mov_b64_e32 v[52:53], 0
	v_mov_b64_e32 v[54:55], 0
	v_mov_b64_e32 v[8:9], 0
	v_mov_b64_e32 v[10:11], 0
	v_mov_b64_e32 v[12:13], 0
	v_mov_b64_e32 v[14:15], 0
	v_mov_b64_e32 v[24:25], 0
	v_mov_b64_e32 v[26:27], 0
	v_mov_b64_e32 v[28:29], 0
	v_mov_b64_e32 v[30:31], 0
	v_mov_b64_e32 v[40:41], 0
	v_mov_b64_e32 v[42:43], 0
	v_mov_b64_e32 v[44:45], 0
	v_mov_b64_e32 v[46:47], 0
	v_mov_b64_e32 v[56:57], 0
	v_mov_b64_e32 v[58:59], 0
	v_mov_b64_e32 v[60:61], 0
	v_mov_b64_e32 v[62:63], 0
	v_mov_b64_e32 v[64:65], 0
	v_mov_b64_e32 v[66:67], 0
	v_mov_b64_e32 v[68:69], 0
	v_mov_b64_e32 v[70:71], 0
	v_mov_b64_e32 v[80:81], 0
	v_mov_b64_e32 v[82:83], 0
	v_mov_b64_e32 v[84:85], 0
	v_mov_b64_e32 v[86:87], 0
	v_mov_b64_e32 v[96:97], 0
	v_mov_b64_e32 v[98:99], 0
	v_mov_b64_e32 v[100:101], 0
	v_mov_b64_e32 v[102:103], 0
	v_mov_b64_e32 v[112:113], 0
	v_mov_b64_e32 v[114:115], 0
	v_mov_b64_e32 v[116:117], 0
	v_mov_b64_e32 v[118:119], 0
	v_mov_b64_e32 v[72:73], 0
	v_mov_b64_e32 v[74:75], 0
	v_mov_b64_e32 v[76:77], 0
	v_mov_b64_e32 v[78:79], 0
	v_mov_b64_e32 v[88:89], 0
	v_mov_b64_e32 v[90:91], 0
	v_mov_b64_e32 v[92:93], 0
	v_mov_b64_e32 v[94:95], 0
	v_mov_b64_e32 v[104:105], 0
	v_mov_b64_e32 v[106:107], 0
	v_mov_b64_e32 v[108:109], 0
	v_mov_b64_e32 v[110:111], 0
	v_mov_b64_e32 v[120:121], 0
	v_mov_b64_e32 v[122:123], 0
	v_mov_b64_e32 v[124:125], 0
	v_mov_b64_e32 v[126:127], 0
	v_xor_b32_e32 v216, 64, v145
	v_xor_b32_e32 v217, 64, v146
	v_xor_b32_e32 v234, 64, v147
	v_add_u32_e32 v235, 0x18000, v144
	v_xor_b32_e32 v244, 64, v235
	s_cmpk_lt_u32 s3, 0x100
	s_cbranch_scc1 .Lst_in_s7
	s_barrier

.LBB0_839:
	s_ashr_i32 s37, s36, 31
	v_cmp_lt_i64_e32 vcc, s[12:13], v[184:185]
	s_lshl_b64 s[12:13], s[36:37], 20
	s_add_u32 s38, s80, s12
	s_addc_u32 s39, s81, s13
	s_and_b64 s[12:13], vcc, exec
	s_cselect_b32 s33, s39, s9
	s_cselect_b32 s37, s38, s8
	s_ashr_i32 s35, s34, 31
	s_lshl_b64 s[12:13], s[34:35], 19
	s_add_u32 s40, s44, s12
	s_addc_u32 s41, s45, s13
	s_and_b64 s[12:13], vcc, exec
	s_cselect_b32 s35, s41, s11
	s_cselect_b32 s64, s40, s10
	s_add_u32 s65, s10, 0x100
	v_mov_b32_e32 v0, 0
	s_addc_u32 s66, s11, 0
	s_mov_b32 s67, -2
	v_mov_b32_e32 v1, v0
	v_mov_b64_e32 v[2:3], 0
	v_mov_b64_e32 v[64:65], 0
	v_mov_b64_e32 v[66:67], 0
	v_mov_b64_e32 v[8:9], 0
	s_waitcnt vmcnt(0)
	v_mov_b64_e32 v[10:11], 0
	v_mov_b64_e32 v[68:69], 0
	v_mov_b64_e32 v[70:71], 0
	v_mov_b64_e32 v[12:13], 0
	v_mov_b64_e32 v[14:15], 0
	v_mov_b64_e32 v[110:111], 0
	v_mov_b64_e32 v[112:113], 0
	v_mov_b64_e32 v[16:17], 0
	v_mov_b64_e32 v[18:19], 0
	v_mov_b64_e32 v[118:119], 0
	v_mov_b64_e32 v[120:121], 0
	v_mov_b64_e32 v[4:5], 0
	v_mov_b64_e32 v[6:7], 0
	v_mov_b64_e32 v[72:73], 0
	v_mov_b64_e32 v[74:75], 0
	v_mov_b64_e32 v[20:21], 0
	v_mov_b64_e32 v[22:23], 0
	v_mov_b64_e32 v[114:115], 0
	v_mov_b64_e32 v[116:117], 0
	v_mov_b64_e32 v[24:25], 0
	v_mov_b64_e32 v[26:27], 0
	v_mov_b64_e32 v[122:123], 0
	v_mov_b64_e32 v[124:125], 0
	v_mov_b64_e32 v[28:29], 0
	v_mov_b64_e32 v[30:31], 0
	v_mov_b64_e32 v[126:127], 0
	v_mov_b64_e32 v[128:129], 0
	v_mov_b64_e32 v[32:33], 0
	v_mov_b64_e32 v[34:35], 0
	v_mov_b64_e32 v[130:131], 0
	v_mov_b64_e32 v[132:133], 0
	v_mov_b64_e32 v[36:37], 0
	v_mov_b64_e32 v[38:39], 0
	v_mov_b64_e32 v[134:135], 0
	v_mov_b64_e32 v[136:137], 0
	v_mov_b64_e32 v[44:45], 0
	v_mov_b64_e32 v[46:47], 0
	v_mov_b64_e32 v[142:143], 0
	v_mov_b64_e32 v[144:145], 0
	v_mov_b64_e32 v[56:57], 0
	v_mov_b64_e32 v[58:59], 0
	v_mov_b64_e32 v[154:155], 0
	v_mov_b64_e32 v[156:157], 0
	v_mov_b64_e32 v[40:41], 0
	v_mov_b64_e32 v[42:43], 0
	v_mov_b64_e32 v[138:139], 0
	v_mov_b64_e32 v[140:141], 0
	v_mov_b64_e32 v[48:49], 0
	v_mov_b64_e32 v[50:51], 0
	v_mov_b64_e32 v[146:147], 0
	v_mov_b64_e32 v[148:149], 0
	v_mov_b64_e32 v[52:53], 0
	v_mov_b64_e32 v[54:55], 0
	v_mov_b64_e32 v[150:151], 0
	v_mov_b64_e32 v[152:153], 0
	v_mov_b64_e32 v[60:61], 0
	v_mov_b64_e32 v[62:63], 0
	v_mov_b64_e32 v[158:159], 0
	v_mov_b64_e32 v[160:161], 0
	v_xor_b32_e32 v220, 64, v171
	v_xor_b32_e32 v221, 64, v173
	v_xor_b32_e32 v238, 64, v175
	v_add_u32_e32 v239, 0x18000, v169
	v_xor_b32_e32 v240, 64, v239
	v_add_u32_e32 v241, 0x1c000, v169
	v_xor_b32_e32 v242, 64, v241
	s_cmpk_lt_u32 s3, 0x100
	s_cbranch_scc1 .Lst_in_s8
	s_barrier

.LBB0_984:
	s_add_u32 s0, s0, 0x160080
	s_addc_u32 s1, s1, 0
	s_add_u32 s39, s14, 0x100
	v_mov_b32_e32 v0, 0
	s_addc_u32 s40, s15, 0
	s_mov_b32 s41, -2
	s_waitcnt lgkmcnt(0)
	v_mov_b32_e32 v1, v0
	v_mov_b64_e32 v[2:3], 0
	v_mov_b64_e32 v[4:5], 0
	v_mov_b64_e32 v[6:7], 0
	s_waitcnt vmcnt(0)
	v_mov_b64_e32 v[16:17], 0
	v_mov_b64_e32 v[18:19], 0
	v_mov_b64_e32 v[20:21], 0
	v_mov_b64_e32 v[22:23], 0
	v_mov_b64_e32 v[32:33], 0
	v_mov_b64_e32 v[34:35], 0
	v_mov_b64_e32 v[36:37], 0
	v_mov_b64_e32 v[38:39], 0
	v_mov_b64_e32 v[48:49], 0
	v_mov_b64_e32 v[50:51], 0
	v_mov_b64_e32 v[52:53], 0
	v_mov_b64_e32 v[54:55], 0
	v_mov_b64_e32 v[8:9], 0
	v_mov_b64_e32 v[10:11], 0
	v_mov_b64_e32 v[12:13], 0
	v_mov_b64_e32 v[14:15], 0
	v_mov_b64_e32 v[24:25], 0
	v_mov_b64_e32 v[26:27], 0
	v_mov_b64_e32 v[28:29], 0
	v_mov_b64_e32 v[30:31], 0
	v_mov_b64_e32 v[40:41], 0
	v_mov_b64_e32 v[42:43], 0
	v_mov_b64_e32 v[44:45], 0
	v_mov_b64_e32 v[46:47], 0
	v_mov_b64_e32 v[56:57], 0
	v_mov_b64_e32 v[58:59], 0
	v_mov_b64_e32 v[60:61], 0
	v_mov_b64_e32 v[62:63], 0
	v_mov_b64_e32 v[64:65], 0
	v_mov_b64_e32 v[66:67], 0
	v_mov_b64_e32 v[68:69], 0
	v_mov_b64_e32 v[70:71], 0
	v_mov_b64_e32 v[80:81], 0
	v_mov_b64_e32 v[82:83], 0
	v_mov_b64_e32 v[84:85], 0
	v_mov_b64_e32 v[86:87], 0
	v_mov_b64_e32 v[96:97], 0
	v_mov_b64_e32 v[98:99], 0
	v_mov_b64_e32 v[100:101], 0
	v_mov_b64_e32 v[102:103], 0
	v_mov_b64_e32 v[112:113], 0
	v_mov_b64_e32 v[114:115], 0
	v_mov_b64_e32 v[116:117], 0
	v_mov_b64_e32 v[118:119], 0
	v_mov_b64_e32 v[72:73], 0
	v_mov_b64_e32 v[74:75], 0
	v_mov_b64_e32 v[76:77], 0
	v_mov_b64_e32 v[78:79], 0
	v_mov_b64_e32 v[88:89], 0
	v_mov_b64_e32 v[90:91], 0
	v_mov_b64_e32 v[92:93], 0
	v_mov_b64_e32 v[94:95], 0
	v_mov_b64_e32 v[104:105], 0
	v_mov_b64_e32 v[106:107], 0
	v_mov_b64_e32 v[108:109], 0
	v_mov_b64_e32 v[110:111], 0
	v_mov_b64_e32 v[120:121], 0
	v_mov_b64_e32 v[122:123], 0
	v_mov_b64_e32 v[124:125], 0
	v_mov_b64_e32 v[126:127], 0
	v_xor_b32_e32 v216, 64, v141
	v_xor_b32_e32 v217, 64, v142
	v_xor_b32_e32 v218, 64, v143
	v_add_u32_e32 v219, 0x18000, v140
	v_xor_b32_e32 v220, 64, v219
	s_cmpk_lt_u32 s3, 0x100
	s_cbranch_scc1 .Lst_in_s9
	s_barrier
